# plus k_pe mini-GEMM with all 32 weight-fragment loads in flight
# baseline (speedup 1.0000x reference)
.Lnk_loop:
	s_mov_b32 s3, 0x1800000
	s_mov_b64 s[4:5], 0x2000
	global_load_dwordx4 v[156:159], v[64:65], off offset:-4096
	global_load_dwordx4 v[160:163], v[64:65], off offset:-3072
	global_load_dwordx4 v[164:167], v[64:65], off offset:-2048
	global_load_dwordx4 v[168:171], v[64:65], off offset:-1024
	global_load_dwordx4 v[172:175], v[64:65], off
	global_load_dwordx4 v[176:179], v[64:65], off offset:1024
	global_load_dwordx4 v[180:183], v[64:65], off offset:2048
	global_load_dwordx4 v[184:187], v[64:65], off offset:3072
	v_lshl_add_u64 v[64:65], v[64:65], 0, s[4:5]
	global_load_dwordx4 v[192:195], v[64:65], off offset:-4096
	global_load_dwordx4 v[196:199], v[64:65], off offset:-3072
	global_load_dwordx4 v[200:203], v[64:65], off offset:-2048
	global_load_dwordx4 v[204:207], v[64:65], off offset:-1024
	global_load_dwordx4 v[208:211], v[64:65], off
	global_load_dwordx4 v[212:215], v[64:65], off offset:1024
	global_load_dwordx4 v[216:219], v[64:65], off offset:2048
	global_load_dwordx4 v[220:223], v[64:65], off offset:3072
	v_lshl_add_u64 v[64:65], v[64:65], 0, s[4:5]
	v_lshl_add_u64 v[30:31], v[62:63], 0, s[0:1]
	v_add_co_u32_e32 v30, vcc, s3, v30
	s_nop 1
	v_addc_co_u32_e32 v31, vcc, 0, v31, vcc
	s_waitcnt vmcnt(8)
	v_mul_f32_e32 v2, v156, v156
	v_mul_f32_e32 v3, v158, v158
	v_fmac_f32_e32 v2, v157, v157
	v_fmac_f32_e32 v3, v159, v159
	v_add_f32_e32 v0, v2, v3
	v_mul_f32_e32 v2, v160, v160
	v_mul_f32_e32 v3, v162, v162
	v_fmac_f32_e32 v2, v161, v161
	v_fmac_f32_e32 v3, v163, v163
	v_add_f32_e32 v2, v2, v3
	v_add_f32_e32 v0, v0, v2
	v_mul_f32_e32 v2, v164, v164
	v_mul_f32_e32 v3, v166, v166
	v_fmac_f32_e32 v2, v165, v165
	v_fmac_f32_e32 v3, v167, v167
	v_add_f32_e32 v2, v2, v3
	v_add_f32_e32 v0, v0, v2
	v_mul_f32_e32 v2, v168, v168
	v_mul_f32_e32 v3, v170, v170
	v_fmac_f32_e32 v2, v169, v169
	v_fmac_f32_e32 v3, v171, v171
	v_add_f32_e32 v2, v2, v3
	v_add_f32_e32 v0, v0, v2
	v_mul_f32_e32 v2, v172, v172
	v_mul_f32_e32 v3, v174, v174
	v_fmac_f32_e32 v2, v173, v173
	v_fmac_f32_e32 v3, v175, v175
	v_add_f32_e32 v2, v2, v3
	v_add_f32_e32 v0, v0, v2
	v_mul_f32_e32 v2, v176, v176
	v_mul_f32_e32 v3, v178, v178
	v_fmac_f32_e32 v2, v177, v177
	v_fmac_f32_e32 v3, v179, v179
	v_add_f32_e32 v2, v2, v3
	v_add_f32_e32 v0, v0, v2
	v_mul_f32_e32 v2, v180, v180
	v_mul_f32_e32 v3, v182, v182
	v_fmac_f32_e32 v2, v181, v181
	v_fmac_f32_e32 v3, v183, v183
	v_add_f32_e32 v2, v2, v3
	v_add_f32_e32 v0, v0, v2
	v_mul_f32_e32 v2, v184, v184
	v_mul_f32_e32 v3, v186, v186
	v_fmac_f32_e32 v2, v185, v185
	v_fmac_f32_e32 v3, v187, v187
	v_add_f32_e32 v2, v2, v3
	v_add_f32_e32 v0, v0, v2
	ds_bpermute_b32 v78, v68, v0
	s_waitcnt lgkmcnt(0)
	v_add_f32_e32 v0, v0, v78
	ds_bpermute_b32 v78, v69, v0
	s_waitcnt lgkmcnt(0)
	v_add_f32_e32 v0, v0, v78
	ds_bpermute_b32 v78, v70, v0
	s_waitcnt lgkmcnt(0)
	v_add_f32_e32 v0, v0, v78
	ds_bpermute_b32 v78, v71, v0
	s_waitcnt lgkmcnt(0)
	v_add_f32_e32 v0, v0, v78
	ds_bpermute_b32 v78, v72, v0
	s_waitcnt lgkmcnt(0)
	v_add_f32_e32 v0, v0, v78
	ds_bpermute_b32 v78, v73, v0
	s_waitcnt lgkmcnt(0)
	v_add_f32_e32 v0, v0, v78
	v_fmamk_f32 v0, v0, 0x3a000000, v147
	v_cmp_gt_f32_e32 vcc, s29, v0
	v_mul_f32_e32 v78, 0x4b800000, v0
	s_nop 0
	v_cndmask_b32_e32 v0, v0, v78, vcc
	v_rsq_f32_e32 v0, v0
	s_nop 0
	v_mul_f32_e32 v78, 0x45800000, v0
	v_cndmask_b32_e32 v0, v0, v78, vcc
	v_mul_f32_e32 v2, v156, v0
	v_mul_f32_e32 v3, v157, v0
	v_mul_f32_e32 v4, v158, v0
	v_mul_f32_e32 v5, v159, v0
	v_mul_f32_e32 v2, v2, v88
	v_mul_f32_e32 v3, v3, v89
	v_mul_f32_e32 v4, v4, v90
	v_mul_f32_e32 v5, v5, v91
	v_cvt_pk_bf16_f32 v224, v2, v3
	v_cvt_pk_bf16_f32 v225, v4, v5
	global_store_dwordx2 v[30:31], v[224:225], off
	ds_write_b64 v55, v[224:225]
	v_mul_f32_e32 v2, v160, v0
	v_mul_f32_e32 v3, v161, v0
	v_mul_f32_e32 v4, v162, v0
	v_mul_f32_e32 v5, v163, v0
	v_mul_f32_e32 v2, v2, v92
	v_mul_f32_e32 v3, v3, v93
	v_mul_f32_e32 v4, v4, v94
	v_mul_f32_e32 v5, v5, v95
	v_cvt_pk_bf16_f32 v226, v2, v3
	v_cvt_pk_bf16_f32 v227, v4, v5
	global_store_dwordx2 v[30:31], v[226:227], off offset:512
	ds_write_b64 v55, v[226:227] offset:512
	v_mul_f32_e32 v2, v164, v0
	v_mul_f32_e32 v3, v165, v0
	v_mul_f32_e32 v4, v166, v0
	v_mul_f32_e32 v5, v167, v0
	v_mul_f32_e32 v2, v2, v96
	v_mul_f32_e32 v3, v3, v97
	v_mul_f32_e32 v4, v4, v98
	v_mul_f32_e32 v5, v5, v99
	v_cvt_pk_bf16_f32 v228, v2, v3
	v_cvt_pk_bf16_f32 v229, v4, v5
	global_store_dwordx2 v[30:31], v[228:229], off offset:1024
	ds_write_b64 v55, v[228:229] offset:1024
	v_mul_f32_e32 v2, v168, v0
	v_mul_f32_e32 v3, v169, v0
	v_mul_f32_e32 v4, v170, v0
	v_mul_f32_e32 v5, v171, v0
	v_mul_f32_e32 v2, v2, v100
	v_mul_f32_e32 v3, v3, v101
	v_mul_f32_e32 v4, v4, v102
	v_mul_f32_e32 v5, v5, v103
	v_cvt_pk_bf16_f32 v230, v2, v3
	v_cvt_pk_bf16_f32 v231, v4, v5
	global_store_dwordx2 v[30:31], v[230:231], off offset:1536
	ds_write_b64 v55, v[230:231] offset:1536
	v_mul_f32_e32 v2, v172, v0
	v_mul_f32_e32 v3, v173, v0
	v_mul_f32_e32 v4, v174, v0
	v_mul_f32_e32 v5, v175, v0
	v_mul_f32_e32 v2, v2, v104
	v_mul_f32_e32 v3, v3, v105
	v_mul_f32_e32 v4, v4, v106
	v_mul_f32_e32 v5, v5, v107
	v_cvt_pk_bf16_f32 v232, v2, v3
	v_cvt_pk_bf16_f32 v233, v4, v5
	global_store_dwordx2 v[30:31], v[232:233], off offset:2048
	ds_write_b64 v55, v[232:233] offset:2048
	v_mul_f32_e32 v2, v176, v0
	v_mul_f32_e32 v3, v177, v0
	v_mul_f32_e32 v4, v178, v0
	v_mul_f32_e32 v5, v179, v0
	v_mul_f32_e32 v2, v2, v108
	v_mul_f32_e32 v3, v3, v109
	v_mul_f32_e32 v4, v4, v110
	v_mul_f32_e32 v5, v5, v111
	v_cvt_pk_bf16_f32 v234, v2, v3
	v_cvt_pk_bf16_f32 v235, v4, v5
	global_store_dwordx2 v[30:31], v[234:235], off offset:2560
	ds_write_b64 v55, v[234:235] offset:2560
	v_mul_f32_e32 v2, v180, v0
	v_mul_f32_e32 v3, v181, v0
	v_mul_f32_e32 v4, v182, v0
	v_mul_f32_e32 v5, v183, v0
	v_mul_f32_e32 v2, v2, v112
	v_mul_f32_e32 v3, v3, v113
	v_mul_f32_e32 v4, v4, v114
	v_mul_f32_e32 v5, v5, v115
	v_cvt_pk_bf16_f32 v236, v2, v3
	v_cvt_pk_bf16_f32 v237, v4, v5
	global_store_dwordx2 v[30:31], v[236:237], off offset:3072
	ds_write_b64 v55, v[236:237] offset:3072
	v_mul_f32_e32 v2, v184, v0
	v_mul_f32_e32 v3, v185, v0
	v_mul_f32_e32 v4, v186, v0
	v_mul_f32_e32 v5, v187, v0
	v_mul_f32_e32 v2, v2, v116
	v_mul_f32_e32 v3, v3, v117
	v_mul_f32_e32 v4, v4, v118
	v_mul_f32_e32 v5, v5, v119
	v_cvt_pk_bf16_f32 v238, v2, v3
	v_cvt_pk_bf16_f32 v239, v4, v5
	global_store_dwordx2 v[30:31], v[238:239], off offset:3584
	ds_write_b64 v55, v[238:239] offset:3584
	s_add_u32 s0, s0, 0x1000
	s_addc_u32 s1, s1, 0
	v_add_u32_e32 v55, 0x1010, v55
	v_lshl_add_u64 v[30:31], v[62:63], 0, s[0:1]
	v_add_co_u32_e32 v30, vcc, s3, v30
	s_nop 1
	v_addc_co_u32_e32 v31, vcc, 0, v31, vcc
	s_waitcnt vmcnt(8)
	v_mul_f32_e32 v2, v192, v192
	v_mul_f32_e32 v3, v194, v194
	v_fmac_f32_e32 v2, v193, v193
	v_fmac_f32_e32 v3, v195, v195
	v_add_f32_e32 v0, v2, v3
	v_mul_f32_e32 v2, v196, v196
	v_mul_f32_e32 v3, v198, v198
	v_fmac_f32_e32 v2, v197, v197
	v_fmac_f32_e32 v3, v199, v199
	v_add_f32_e32 v2, v2, v3
	v_add_f32_e32 v0, v0, v2
	v_mul_f32_e32 v2, v200, v200
	v_mul_f32_e32 v3, v202, v202
	v_fmac_f32_e32 v2, v201, v201
	v_fmac_f32_e32 v3, v203, v203
	v_add_f32_e32 v2, v2, v3
	v_add_f32_e32 v0, v0, v2
	v_mul_f32_e32 v2, v204, v204
	v_mul_f32_e32 v3, v206, v206
	v_fmac_f32_e32 v2, v205, v205
	v_fmac_f32_e32 v3, v207, v207
	v_add_f32_e32 v2, v2, v3
	v_add_f32_e32 v0, v0, v2
	v_mul_f32_e32 v2, v208, v208
	v_mul_f32_e32 v3, v210, v210
	v_fmac_f32_e32 v2, v209, v209
	v_fmac_f32_e32 v3, v211, v211
	v_add_f32_e32 v2, v2, v3
	v_add_f32_e32 v0, v0, v2
	v_mul_f32_e32 v2, v212, v212
	v_mul_f32_e32 v3, v214, v214
	v_fmac_f32_e32 v2, v213, v213
	v_fmac_f32_e32 v3, v215, v215
	v_add_f32_e32 v2, v2, v3
	v_add_f32_e32 v0, v0, v2
	v_mul_f32_e32 v2, v216, v216
	v_mul_f32_e32 v3, v218, v218
	v_fmac_f32_e32 v2, v217, v217
	v_fmac_f32_e32 v3, v219, v219
	v_add_f32_e32 v2, v2, v3
	v_add_f32_e32 v0, v0, v2
	v_mul_f32_e32 v2, v220, v220
	v_mul_f32_e32 v3, v222, v222
	v_fmac_f32_e32 v2, v221, v221
	v_fmac_f32_e32 v3, v223, v223
	v_add_f32_e32 v2, v2, v3
	v_add_f32_e32 v0, v0, v2
	ds_bpermute_b32 v78, v68, v0
	s_waitcnt lgkmcnt(0)
	v_add_f32_e32 v0, v0, v78
	ds_bpermute_b32 v78, v69, v0
	s_waitcnt lgkmcnt(0)
	v_add_f32_e32 v0, v0, v78
	ds_bpermute_b32 v78, v70, v0
	s_waitcnt lgkmcnt(0)
	v_add_f32_e32 v0, v0, v78
	ds_bpermute_b32 v78, v71, v0
	s_waitcnt lgkmcnt(0)
	v_add_f32_e32 v0, v0, v78
	ds_bpermute_b32 v78, v72, v0
	s_waitcnt lgkmcnt(0)
	v_add_f32_e32 v0, v0, v78
	ds_bpermute_b32 v78, v73, v0
	s_waitcnt lgkmcnt(0)
	v_add_f32_e32 v0, v0, v78
	v_fmamk_f32 v0, v0, 0x3a000000, v147
	v_cmp_gt_f32_e32 vcc, s29, v0
	v_mul_f32_e32 v78, 0x4b800000, v0
	s_nop 0
	v_cndmask_b32_e32 v0, v0, v78, vcc
	v_rsq_f32_e32 v0, v0
	s_nop 0
	v_mul_f32_e32 v78, 0x45800000, v0
	v_cndmask_b32_e32 v0, v0, v78, vcc
	v_mul_f32_e32 v2, v192, v0
	v_mul_f32_e32 v3, v193, v0
	v_mul_f32_e32 v4, v194, v0
	v_mul_f32_e32 v5, v195, v0
	v_mul_f32_e32 v2, v2, v88
	v_mul_f32_e32 v3, v3, v89
	v_mul_f32_e32 v4, v4, v90
	v_mul_f32_e32 v5, v5, v91
	v_cvt_pk_bf16_f32 v120, v2, v3
	v_cvt_pk_bf16_f32 v121, v4, v5
	global_store_dwordx2 v[30:31], v[120:121], off
	ds_write_b64 v55, v[120:121]
	v_mul_f32_e32 v2, v196, v0
	v_mul_f32_e32 v3, v197, v0
	v_mul_f32_e32 v4, v198, v0
	v_mul_f32_e32 v5, v199, v0
	v_mul_f32_e32 v2, v2, v92
	v_mul_f32_e32 v3, v3, v93
	v_mul_f32_e32 v4, v4, v94
	v_mul_f32_e32 v5, v5, v95
	v_cvt_pk_bf16_f32 v122, v2, v3
	v_cvt_pk_bf16_f32 v123, v4, v5
	global_store_dwordx2 v[30:31], v[122:123], off offset:512
	ds_write_b64 v55, v[122:123] offset:512
	v_mul_f32_e32 v2, v200, v0
	v_mul_f32_e32 v3, v201, v0
	v_mul_f32_e32 v4, v202, v0
	v_mul_f32_e32 v5, v203, v0
	v_mul_f32_e32 v2, v2, v96
	v_mul_f32_e32 v3, v3, v97
	v_mul_f32_e32 v4, v4, v98
	v_mul_f32_e32 v5, v5, v99
	v_cvt_pk_bf16_f32 v124, v2, v3
	v_cvt_pk_bf16_f32 v125, v4, v5
	global_store_dwordx2 v[30:31], v[124:125], off offset:1024
	ds_write_b64 v55, v[124:125] offset:1024
	v_mul_f32_e32 v2, v204, v0
	v_mul_f32_e32 v3, v205, v0
	v_mul_f32_e32 v4, v206, v0
	v_mul_f32_e32 v5, v207, v0
	v_mul_f32_e32 v2, v2, v100
	v_mul_f32_e32 v3, v3, v101
	v_mul_f32_e32 v4, v4, v102
	v_mul_f32_e32 v5, v5, v103
	v_cvt_pk_bf16_f32 v126, v2, v3
	v_cvt_pk_bf16_f32 v127, v4, v5
	global_store_dwordx2 v[30:31], v[126:127], off offset:1536
	ds_write_b64 v55, v[126:127] offset:1536
	v_mul_f32_e32 v2, v208, v0
	v_mul_f32_e32 v3, v209, v0
	v_mul_f32_e32 v4, v210, v0
	v_mul_f32_e32 v5, v211, v0
	v_mul_f32_e32 v2, v2, v104
	v_mul_f32_e32 v3, v3, v105
	v_mul_f32_e32 v4, v4, v106
	v_mul_f32_e32 v5, v5, v107
	v_cvt_pk_bf16_f32 v128, v2, v3
	v_cvt_pk_bf16_f32 v129, v4, v5
	global_store_dwordx2 v[30:31], v[128:129], off offset:2048
	ds_write_b64 v55, v[128:129] offset:2048
	v_mul_f32_e32 v2, v212, v0
	v_mul_f32_e32 v3, v213, v0
	v_mul_f32_e32 v4, v214, v0
	v_mul_f32_e32 v5, v215, v0
	v_mul_f32_e32 v2, v2, v108
	v_mul_f32_e32 v3, v3, v109
	v_mul_f32_e32 v4, v4, v110
	v_mul_f32_e32 v5, v5, v111
	v_cvt_pk_bf16_f32 v130, v2, v3
	v_cvt_pk_bf16_f32 v131, v4, v5
	global_store_dwordx2 v[30:31], v[130:131], off offset:2560
	ds_write_b64 v55, v[130:131] offset:2560
	v_mul_f32_e32 v2, v216, v0
	v_mul_f32_e32 v3, v217, v0
	v_mul_f32_e32 v4, v218, v0
	v_mul_f32_e32 v5, v219, v0
	v_mul_f32_e32 v2, v2, v112
	v_mul_f32_e32 v3, v3, v113
	v_mul_f32_e32 v4, v4, v114
	v_mul_f32_e32 v5, v5, v115
	v_cvt_pk_bf16_f32 v132, v2, v3
	v_cvt_pk_bf16_f32 v133, v4, v5
	global_store_dwordx2 v[30:31], v[132:133], off offset:3072
	ds_write_b64 v55, v[132:133] offset:3072
	v_mul_f32_e32 v2, v220, v0
	v_mul_f32_e32 v3, v221, v0
	v_mul_f32_e32 v4, v222, v0
	v_mul_f32_e32 v5, v223, v0
	v_mul_f32_e32 v2, v2, v116
	v_mul_f32_e32 v3, v3, v117
	v_mul_f32_e32 v4, v4, v118
	v_mul_f32_e32 v5, v5, v119
	v_cvt_pk_bf16_f32 v134, v2, v3
	v_cvt_pk_bf16_f32 v135, v4, v5
	global_store_dwordx2 v[30:31], v[134:135], off offset:3584
	ds_write_b64 v55, v[134:135] offset:3584
	s_add_u32 s0, s0, 0x1000
	s_addc_u32 s1, s1, 0
	v_add_u32_e32 v55, 0x1010, v55
	s_cmpk_eq_i32 s0, 0x4000
	s_cbranch_scc0 .Lnk_loop
	v_mov_b32_e32 v2, 0
	s_mov_b32 s0, 0
	v_mov_b64_e32 v[62:63], v[60:61]
	v_mov_b32_e32 v0, v76
	v_mov_b32_e32 v3, v2
	v_mov_b32_e32 v4, v2
	v_mov_b32_e32 v5, v2
	v_mov_b32_e32 v6, v2
	v_mov_b32_e32 v7, v2
	v_mov_b32_e32 v8, v2
	v_mov_b32_e32 v9, v2
	v_mov_b32_e32 v10, v2
	v_mov_b32_e32 v11, v2
	v_mov_b32_e32 v12, v2
	v_mov_b32_e32 v13, v2
	v_mov_b32_e32 v14, v2
	v_mov_b32_e32 v15, v2
	v_mov_b32_e32 v16, v2
	v_mov_b32_e32 v17, v2
	v_mov_b32_e32 v18, v2
	v_mov_b32_e32 v19, v2
	v_mov_b32_e32 v20, v2
	v_mov_b32_e32 v21, v2
	v_mov_b32_e32 v22, v2
	v_mov_b32_e32 v23, v2
	v_mov_b32_e32 v24, v2
	v_mov_b32_e32 v25, v2
	v_mov_b32_e32 v26, v2
	v_mov_b32_e32 v27, v2
	v_mov_b32_e32 v28, v2
	v_mov_b32_e32 v29, v2
	v_mov_b32_e32 v30, v2
	v_mov_b32_e32 v31, v2
	v_mov_b32_e32 v32, v2
	v_mov_b32_e32 v33, v2
	s_waitcnt lgkmcnt(0)
	s_barrier
	v_ashrrev_i32_e32 v65, 31, v58
	v_mov_b32_e32 v64, v58
	v_lshlrev_b64 v[82:83], 1, v[64:65]
	v_lshl_add_u64 v[84:85], v[34:35], 0, v[82:83]
	v_lshl_add_u64 v[86:87], v[36:37], 0, v[82:83]
	global_load_dwordx4 v[88:91], v[84:85], off
	global_load_dwordx4 v[164:167], v[86:87], off
	global_load_dwordx4 v[92:95], v[62:63], off
	global_load_dwordx4 v[168:171], v[86:87], off offset:32
	global_load_dwordx4 v[96:99], v[62:63], off offset:32
	global_load_dwordx4 v[172:175], v[86:87], off offset:64
	global_load_dwordx4 v[100:103], v[62:63], off offset:64
	global_load_dwordx4 v[176:179], v[86:87], off offset:96
	global_load_dwordx4 v[104:107], v[84:85], off offset:128
	global_load_dwordx4 v[180:183], v[86:87], off offset:128
	global_load_dwordx4 v[108:111], v[62:63], off offset:128
	global_load_dwordx4 v[184:187], v[86:87], off offset:160
	global_load_dwordx4 v[112:115], v[62:63], off offset:160
	global_load_dwordx4 v[192:195], v[86:87], off offset:192
	global_load_dwordx4 v[116:119], v[62:63], off offset:192
	global_load_dwordx4 v[196:199], v[86:87], off offset:224
	global_load_dwordx4 v[120:123], v[84:85], off offset:256
	global_load_dwordx4 v[200:203], v[86:87], off offset:256
	global_load_dwordx4 v[124:127], v[62:63], off offset:256
	global_load_dwordx4 v[204:207], v[86:87], off offset:288
	global_load_dwordx4 v[128:131], v[62:63], off offset:288
	global_load_dwordx4 v[208:211], v[86:87], off offset:320
	global_load_dwordx4 v[132:135], v[62:63], off offset:320
	global_load_dwordx4 v[212:215], v[86:87], off offset:352
	global_load_dwordx4 v[136:139], v[84:85], off offset:384
	global_load_dwordx4 v[216:219], v[86:87], off offset:384
	global_load_dwordx4 v[140:143], v[62:63], off offset:384
	global_load_dwordx4 v[220:223], v[86:87], off offset:416
	global_load_dwordx4 v[156:159], v[62:63], off offset:416
	global_load_dwordx4 v[224:227], v[86:87], off offset:448
	global_load_dwordx4 v[160:163], v[62:63], off offset:448
	global_load_dwordx4 v[228:231], v[86:87], off offset:480
	ds_read_b128 v[78:81], v0
	ds_read_b128 v[82:85], v0 offset:32
	s_waitcnt vmcnt(30) lgkmcnt(1)
	v_mfma_f32_32x32x16_bf16 v[2:17], v[88:91], v[78:81], v[2:17]
	v_mfma_f32_32x32x16_bf16 v[18:33], v[164:167], v[78:81], v[18:33]
	ds_read_b128 v[78:81], v0 offset:64
	s_waitcnt vmcnt(28) lgkmcnt(1)
	v_mfma_f32_32x32x16_bf16 v[2:17], v[92:95], v[82:85], v[2:17]
	v_mfma_f32_32x32x16_bf16 v[18:33], v[168:171], v[82:85], v[18:33]
	ds_read_b128 v[82:85], v0 offset:96
	s_waitcnt vmcnt(26) lgkmcnt(1)
	v_mfma_f32_32x32x16_bf16 v[2:17], v[96:99], v[78:81], v[2:17]
	v_mfma_f32_32x32x16_bf16 v[18:33], v[172:175], v[78:81], v[18:33]
	ds_read_b128 v[78:81], v0 offset:128
	s_waitcnt vmcnt(24) lgkmcnt(1)
	v_mfma_f32_32x32x16_bf16 v[2:17], v[100:103], v[82:85], v[2:17]
	v_mfma_f32_32x32x16_bf16 v[18:33], v[176:179], v[82:85], v[18:33]
	ds_read_b128 v[82:85], v0 offset:160
	s_waitcnt vmcnt(22) lgkmcnt(1)
	v_mfma_f32_32x32x16_bf16 v[2:17], v[104:107], v[78:81], v[2:17]
	v_mfma_f32_32x32x16_bf16 v[18:33], v[180:183], v[78:81], v[18:33]
	ds_read_b128 v[78:81], v0 offset:192
	s_waitcnt vmcnt(20) lgkmcnt(1)
	v_mfma_f32_32x32x16_bf16 v[2:17], v[108:111], v[82:85], v[2:17]
	v_mfma_f32_32x32x16_bf16 v[18:33], v[184:187], v[82:85], v[18:33]
	ds_read_b128 v[82:85], v0 offset:224
	s_waitcnt vmcnt(18) lgkmcnt(1)
	v_mfma_f32_32x32x16_bf16 v[2:17], v[112:115], v[78:81], v[2:17]
	v_mfma_f32_32x32x16_bf16 v[18:33], v[192:195], v[78:81], v[18:33]
	ds_read_b128 v[78:81], v0 offset:256
	s_waitcnt vmcnt(16) lgkmcnt(1)
	v_mfma_f32_32x32x16_bf16 v[2:17], v[116:119], v[82:85], v[2:17]
	v_mfma_f32_32x32x16_bf16 v[18:33], v[196:199], v[82:85], v[18:33]
	ds_read_b128 v[82:85], v0 offset:288
	s_waitcnt vmcnt(14) lgkmcnt(1)
	v_mfma_f32_32x32x16_bf16 v[2:17], v[120:123], v[78:81], v[2:17]
	v_mfma_f32_32x32x16_bf16 v[18:33], v[200:203], v[78:81], v[18:33]
	ds_read_b128 v[78:81], v0 offset:320
	s_waitcnt vmcnt(12) lgkmcnt(1)
	v_mfma_f32_32x32x16_bf16 v[2:17], v[124:127], v[82:85], v[2:17]
	v_mfma_f32_32x32x16_bf16 v[18:33], v[204:207], v[82:85], v[18:33]
	ds_read_b128 v[82:85], v0 offset:352
	s_waitcnt vmcnt(10) lgkmcnt(1)
	v_mfma_f32_32x32x16_bf16 v[2:17], v[128:131], v[78:81], v[2:17]
	v_mfma_f32_32x32x16_bf16 v[18:33], v[208:211], v[78:81], v[18:33]
	ds_read_b128 v[78:81], v0 offset:384
	s_waitcnt vmcnt(8) lgkmcnt(1)
	v_mfma_f32_32x32x16_bf16 v[2:17], v[132:135], v[82:85], v[2:17]
	v_mfma_f32_32x32x16_bf16 v[18:33], v[212:215], v[82:85], v[18:33]
	ds_read_b128 v[82:85], v0 offset:416
	s_waitcnt vmcnt(6) lgkmcnt(1)
	v_mfma_f32_32x32x16_bf16 v[2:17], v[136:139], v[78:81], v[2:17]
	v_mfma_f32_32x32x16_bf16 v[18:33], v[216:219], v[78:81], v[18:33]
	ds_read_b128 v[78:81], v0 offset:448
	s_waitcnt vmcnt(4) lgkmcnt(1)
	v_mfma_f32_32x32x16_bf16 v[2:17], v[140:143], v[82:85], v[2:17]
	v_mfma_f32_32x32x16_bf16 v[18:33], v[220:223], v[82:85], v[18:33]
	ds_read_b128 v[82:85], v0 offset:480
	s_waitcnt vmcnt(2) lgkmcnt(1)
	v_mfma_f32_32x32x16_bf16 v[2:17], v[156:159], v[78:81], v[2:17]
	v_mfma_f32_32x32x16_bf16 v[18:33], v[224:227], v[78:81], v[18:33]
	s_waitcnt vmcnt(0) lgkmcnt(0)
	v_mfma_f32_32x32x16_bf16 v[2:17], v[160:163], v[82:85], v[2:17]
	v_mfma_f32_32x32x16_bf16 v[18:33], v[228:231], v[82:85], v[18:33]
	v_add_u32_e32 v0, 0x200, v0
	v_lshl_add_u64 v[62:63], s[34:35], 2, v[62:63]
	s_movk_i32 s0, 0x100
	s_cmpk_eq_i32 s0, 0x100
	s_barrier
	s_nop 6
	ds_write2st64_b32 v59, v2, v3 offset1:1
	s_nop 1
	ds_write2st64_b32 v59, v18, v19 offset0:16 offset1:17
	ds_write2st64_b32 v59, v4, v5 offset0:2 offset1:3
	ds_write2st64_b32 v59, v20, v21 offset0:18 offset1:19
	ds_write2st64_b32 v59, v6, v7 offset0:4 offset1:5
	ds_write2st64_b32 v59, v22, v23 offset0:20 offset1:21
	ds_write2st64_b32 v59, v8, v9 offset0:6 offset1:7
	ds_write2st64_b32 v59, v24, v25 offset0:22 offset1:23
	ds_write2st64_b32 v59, v10, v11 offset0:8 offset1:9
	ds_write2st64_b32 v59, v26, v27 offset0:24 offset1:25
	ds_write2st64_b32 v59, v12, v13 offset0:10 offset1:11
	ds_write2st64_b32 v59, v28, v29 offset0:26 offset1:27
	ds_write2st64_b32 v59, v14, v15 offset0:12 offset1:13
	ds_write2st64_b32 v59, v30, v31 offset0:28 offset1:29
	ds_write2st64_b32 v59, v16, v17 offset0:14 offset1:15
	ds_write2st64_b32 v59, v32, v33 offset0:30 offset1:31
	v_lshl_or_b32 v2, s2, 5, v66
	v_ashrrev_i32_e32 v3, 31, v2
	v_lshlrev_b64 v[4:5], 8, v[2:3]
	v_lshl_add_u64 v[4:5], s[12:13], 0, v[4:5]
	v_lshl_add_u64 v[6:7], v[48:49], 3, v[4:5]
	s_waitcnt lgkmcnt(0)
	s_barrier
	flat_load_dwordx2 v[6:7], v[6:7]
	v_add_u32_e32 v0, v67, v74
	ds_read2st64_b32 v[8:9], v0 offset1:16
	ds_read2st64_b32 v[10:11], v0 offset0:17 offset1:32
	ds_read2st64_b32 v[12:13], v0 offset0:33 offset1:48
	ds_read2st64_b32 v[14:15], v0 offset0:49 offset1:64
	ds_read2st64_b32 v[16:17], v0 offset0:65 offset1:80
	ds_read2st64_b32 v[18:19], v0 offset0:81 offset1:96
	ds_read2st64_b32 v[20:21], v0 offset0:97 offset1:112
	ds_read2st64_b32 v[22:23], v0 offset0:113 offset1:128
	ds_read2st64_b32 v[24:25], v0 offset0:129 offset1:144
	ds_read2st64_b32 v[26:27], v0 offset0:145 offset1:160
	ds_read2st64_b32 v[28:29], v0 offset0:161 offset1:176
	ds_read2st64_b32 v[30:31], v0 offset0:177 offset1:192
	ds_read2st64_b32 v[32:33], v0 offset0:193 offset1:208
	ds_read2st64_b32 v[62:63], v0 offset0:209 offset1:224
	ds_read2st64_b32 v[64:65], v0 offset0:225 offset1:240
	s_waitcnt lgkmcnt(0)
	v_add_f32_e32 v78, 0, v9
	v_add_f32_e32 v55, 0, v8
	v_add_f32_e32 v13, v78, v13
	v_add_f32_e32 v11, v55, v11
	v_add_f32_e32 v13, v13, v17
	v_add_f32_e32 v11, v11, v15
	v_add_f32_e32 v13, v13, v21
	v_add_f32_e32 v11, v11, v19
	v_add_f32_e32 v13, v13, v25
	v_add_f32_e32 v11, v11, v23
	v_add_f32_e32 v13, v13, v29
	v_add_f32_e32 v11, v11, v27
	v_add_f32_e32 v13, v13, v33
	v_add_f32_e32 v11, v11, v31
	v_add_f32_e32 v13, v13, v65
	s_movk_i32 s0, 0xb00
	v_add_f32_e32 v11, v11, v63
	v_mad_i64_i32 v[2:3], s[0:1], v2, s0, v[4:5]
	s_mov_b64 s[0:1], 0xd000100
	s_nop 0
	v_lshl_add_u64 v[2:3], v[2:3], 0, s[0:1]
	v_lshl_add_u64 v[8:9], v[48:49], 1, v[2:3]
	v_lshl_add_u64 v[4:5], v[50:51], 3, v[4:5]
	v_readlane_b32 s0, v252, 1
	s_add_i32 s2, s2, s0
	s_cmpk_gt_i32 s2, 0xff
	v_lshl_add_u64 v[2:3], v[50:51], 1, v[2:3]
	v_add_u32_e32 v54, s6, v54
	v_readlane_b32 s1, v252, 2
	s_waitcnt vmcnt(0)
	v_mul_f32_e32 v15, v13, v7
	v_mul_f32_e32 v7, v11, v7
	v_fma_f32 v11, v11, v6, -v15
	v_fmac_f32_e32 v7, v13, v6
	v_bfe_u32 v6, v11, 16, 1
	v_bfe_u32 v13, v7, 16, 1
	v_add3_u32 v6, v11, v6, s33
	v_add3_u32 v7, v7, v13, s33
	v_lshrrev_b32_e32 v6, 16, v6
	v_lshrrev_b32_e32 v7, 16, v7
	flat_store_short v[8:9], v6
	flat_store_short v[8:9], v7 offset:64
	flat_store_short v[8:9], v6 offset:384
	flat_store_short v[8:9], v7 offset:448
	flat_store_short v[8:9], v6 offset:768
	flat_store_short v[8:9], v7 offset:832
	flat_store_short v[8:9], v6 offset:1152
	flat_store_short v[8:9], v7 offset:1216
	flat_store_short v[8:9], v6 offset:1536
	flat_store_short v[8:9], v7 offset:1600
	flat_store_short v[8:9], v6 offset:1920
	flat_store_short v[8:9], v7 offset:1984
	flat_store_short v[8:9], v6 offset:2304
	flat_store_short v[8:9], v7 offset:2368
	flat_store_short v[8:9], v6 offset:2688
	flat_store_short v[8:9], v7 offset:2752
	flat_load_dwordx2 v[4:5], v[4:5]
	ds_read_b32 v6, v77
	ds_read_b32 v0, v0 offset:61696
	v_add_f32_e32 v7, 0, v10
	v_add_f32_e32 v7, v7, v14
	v_add_f32_e32 v7, v7, v18
	s_waitcnt lgkmcnt(0)
	v_add_f32_e32 v6, 0, v6
	v_add_f32_e32 v6, v6, v12
	v_add_f32_e32 v6, v6, v16
	v_add_f32_e32 v7, v7, v22
	v_add_f32_e32 v6, v6, v20
	v_add_f32_e32 v7, v7, v26
	v_add_f32_e32 v6, v6, v24
	v_add_f32_e32 v7, v7, v30
	v_add_f32_e32 v6, v6, v28
	v_add_f32_e32 v7, v7, v62
	v_add_f32_e32 v6, v6, v32
	v_add_f32_e32 v0, v7, v0
	v_add_f32_e32 v6, v6, v64
	s_waitcnt vmcnt(0)
	v_mul_f32_e32 v7, v0, v5
	v_mul_f32_e32 v5, v6, v5
	v_fma_f32 v6, v6, v4, -v7
	v_fmac_f32_e32 v5, v0, v4
	v_bfe_u32 v0, v6, 16, 1
	v_bfe_u32 v4, v5, 16, 1
	v_add3_u32 v0, v6, v0, s33
	v_add3_u32 v4, v5, v4, s33
	v_lshrrev_b32_e32 v0, 16, v0
	v_lshrrev_b32_e32 v4, 16, v4
	flat_store_short v[2:3], v0
	flat_store_short v[2:3], v4 offset:64
	flat_store_short v[2:3], v0 offset:384
	flat_store_short v[2:3], v4 offset:448
	flat_store_short v[2:3], v0 offset:768
	flat_store_short v[2:3], v4 offset:832
	flat_store_short v[2:3], v0 offset:1152
	flat_store_short v[2:3], v4 offset:1216
	flat_store_short v[2:3], v0 offset:1536
	flat_store_short v[2:3], v4 offset:1600
	flat_store_short v[2:3], v0 offset:1920
	flat_store_short v[2:3], v4 offset:1984
	flat_store_short v[2:3], v0 offset:2304
	flat_store_short v[2:3], v4 offset:2368
	flat_store_short v[2:3], v0 offset:2688
	flat_store_short v[2:3], v4 offset:2752
	s_waitcnt lgkmcnt(0)
	s_barrier
	s_cbranch_scc0 .LBB2_716
	v_readlane_b32 s2, v254, 41
	v_readlane_b32 s3, v254, 42
